# GEMM setprio flips deleted + static s_setprio 1 for waves 0-3 (mirror of v035)
# speedup vs baseline: 1.0138x; 1.0138x over previous
; #define LAS __attribute__((address_space(3)))
; __device__ __forceinline__ int otid() { int t = threadIdx.x; asm volatile("" : "+v"(t)); return t; }
; template <class Epi>
; __device__ __forceinline__ void gemm_phase(LAS unsigned char* lds, const Gemm g, const StaticOrder& S, const Epi& E) {
;     const int tid = otid(), wid = __builtin_amdgcn_readfirstlane(tid >> 6), lane = tid & 63, wr = wid >> 2, wc = wid & 3, fr = lane & 15, fq = lane >> 4;
; __global__ void __launch_bounds__(512, 2) mega_fwd(Params p) {
;     extern __shared__ __attribute__((aligned(16))) unsigned char shm[];
;     LAS unsigned char* lds = (LAS unsigned char*)shm;
_Z8mega_fwd6Params:
	v_readfirstlane_b32 s101, v0
	s_and_b32 s101, s101, 0x3ff
	s_lshr_b32 s101, s101, 6
	s_cmp_lt_u32 s101, 4
	s_cbranch_scc0 .Lprio_done
	s_setprio 1
